# gate_up K-loop: 3/5 split of the LDS-DMA pieces between the two load segments (was 2/6), vmcnt 8/7
# baseline (speedup 1.0000x reference)
.LBB0_98:
	s_add_u32 s18, s44, 0xfffc0080
	s_addc_u32 s19, s45, -1
	s_add_i32 s46, 0, 0x10000
	s_cmp_eq_u32 s15, 12
	s_cselect_b32 s25, s7, s19
	s_cselect_b32 s24, s10, s18
	s_cselect_b32 s23, s5, s14
	s_cselect_b32 s22, s11, s13
	s_add_u32 s100, s44, 0xfffc0000
	s_addc_u32 s101, s45, -1
	s_mov_b32 m0, s51
	s_nop 0
	global_load_lds_dwordx4 v140, s[100:101]
	s_add_i32 s47, 0, 0x14000
	ds_read_b128 v[156:159], v240
	ds_read_b128 v[160:163], v240 offset:1024
	ds_read_b128 v[164:167], v240 offset:2048
	ds_read_b128 v[168:171], v240 offset:3072
	ds_read_b128 v[172:175], v240 offset:16384
	ds_read_b128 v[176:179], v240 offset:17408
	ds_read_b128 v[180:183], v240 offset:18432
	ds_read_b128 v[184:187], v240 offset:19456
	s_add_i32 m0, s29, 0xc000
	ds_read_b128 v[208:211], v155
	ds_read_b128 v[212:215], v155 offset:1024
	ds_read_b128 v[216:219], v155 offset:2048
	ds_read_b128 v[220:223], v155 offset:3072
	ds_read_b128 v[224:227], v155 offset:4096
	ds_read_b128 v[228:231], v155 offset:5120
	ds_read_b128 v[232:235], v155 offset:6144
	ds_read_b128 v[236:239], v155 offset:7168
	global_load_lds_dwordx4 v144, s[44:45]
	s_add_i32 m0, s29, 0xe000
	s_nop 0
	global_load_lds_dwordx4 v146, s[44:45]
	s_waitcnt vmcnt(8)
	s_waitcnt lgkmcnt(0)
	s_barrier
	s_setprio 1
	s_waitcnt lgkmcnt(0)
	v_mfma_f32_16x16x32_bf16 v[128:131], v[156:159], v[208:211], v[128:131]
	v_mfma_f32_16x16x32_bf16 v[120:123], v[164:167], v[208:211], v[120:123]
	v_mfma_f32_16x16x32_bf16 v[112:115], v[156:159], v[216:219], v[112:115]
	v_mfma_f32_16x16x32_bf16 v[104:107], v[164:167], v[216:219], v[104:107]
	v_mfma_f32_16x16x32_bf16 v[96:99], v[156:159], v[224:227], v[96:99]
	v_mfma_f32_16x16x32_bf16 v[88:91], v[164:167], v[224:227], v[88:91]
	v_mfma_f32_16x16x32_bf16 v[80:83], v[156:159], v[232:235], v[80:83]
	v_mfma_f32_16x16x32_bf16 v[72:75], v[164:167], v[232:235], v[72:75]
	v_mfma_f32_16x16x32_bf16 v[128:131], v[160:163], v[212:215], v[128:131]
	v_mfma_f32_16x16x32_bf16 v[120:123], v[168:171], v[212:215], v[120:123]
	v_mfma_f32_16x16x32_bf16 v[112:115], v[160:163], v[220:223], v[112:115]
	v_mfma_f32_16x16x32_bf16 v[104:107], v[168:171], v[220:223], v[104:107]
	v_mfma_f32_16x16x32_bf16 v[96:99], v[160:163], v[228:231], v[96:99]
	v_mfma_f32_16x16x32_bf16 v[88:91], v[168:171], v[228:231], v[88:91]
	v_mfma_f32_16x16x32_bf16 v[80:83], v[160:163], v[236:239], v[80:83]
	v_mfma_f32_16x16x32_bf16 v[72:75], v[168:171], v[236:239], v[72:75]
	s_setprio 0
	s_setprio 1
	v_mfma_f32_16x16x32_bf16 v[124:127], v[172:175], v[208:211], v[124:127]
	v_mfma_f32_16x16x32_bf16 v[116:119], v[180:183], v[208:211], v[116:119]
	v_mfma_f32_16x16x32_bf16 v[108:111], v[172:175], v[216:219], v[108:111]
	v_mfma_f32_16x16x32_bf16 v[100:103], v[180:183], v[216:219], v[100:103]
	v_mfma_f32_16x16x32_bf16 v[92:95], v[172:175], v[224:227], v[92:95]
	v_mfma_f32_16x16x32_bf16 v[84:87], v[180:183], v[224:227], v[84:87]
	v_mfma_f32_16x16x32_bf16 v[76:79], v[172:175], v[232:235], v[76:79]
	v_mfma_f32_16x16x32_bf16 v[68:71], v[180:183], v[232:235], v[68:71]
	v_mfma_f32_16x16x32_bf16 v[124:127], v[176:179], v[212:215], v[124:127]
	v_mfma_f32_16x16x32_bf16 v[116:119], v[184:187], v[212:215], v[116:119]
	v_mfma_f32_16x16x32_bf16 v[108:111], v[176:179], v[220:223], v[108:111]
	v_mfma_f32_16x16x32_bf16 v[100:103], v[184:187], v[220:223], v[100:103]
	v_mfma_f32_16x16x32_bf16 v[92:95], v[176:179], v[228:231], v[92:95]
	v_mfma_f32_16x16x32_bf16 v[84:87], v[184:187], v[228:231], v[84:87]
	v_mfma_f32_16x16x32_bf16 v[76:79], v[176:179], v[236:239], v[76:79]
	v_mfma_f32_16x16x32_bf16 v[68:71], v[184:187], v[236:239], v[68:71]
	s_setprio 0
	s_barrier
	s_add_i32 s18, s46, s28
	s_mov_b32 m0, s18
	ds_read_b128 v[208:211], v155 offset:16384
	ds_read_b128 v[212:215], v155 offset:17408
	ds_read_b128 v[216:219], v155 offset:18432
	ds_read_b128 v[220:223], v155 offset:19456
	ds_read_b128 v[224:227], v155 offset:20480
	ds_read_b128 v[228:231], v155 offset:21504
	ds_read_b128 v[232:235], v155 offset:22528
	ds_read_b128 v[236:239], v155 offset:23552
	global_load_lds_dwordx4 v2, s[22:23]
	s_add_i32 m0, s18, 0x2000
	s_add_u32 s18, s22, 0x40000
	s_addc_u32 s19, s23, 0
	s_add_i32 s46, s47, s28
	global_load_lds_dwordx4 v142, s[22:23]
	s_mov_b32 m0, s46
	s_nop 0
	global_load_lds_dwordx4 v2, s[18:19]
	s_add_i32 m0, s46, 0x2000
	s_nop 0
	global_load_lds_dwordx4 v142, s[18:19]
	s_mov_b32 m0, s29
	s_nop 0
	global_load_lds_dwordx4 v0, s[24:25]
	s_waitcnt vmcnt(7)
	s_waitcnt lgkmcnt(0)
	s_barrier
	s_setprio 1
	s_waitcnt lgkmcnt(0)
	v_mfma_f32_16x16x32_bf16 v[64:67], v[156:159], v[208:211], v[64:67]
	v_mfma_f32_16x16x32_bf16 v[56:59], v[164:167], v[208:211], v[56:59]
	v_mfma_f32_16x16x32_bf16 v[48:51], v[156:159], v[216:219], v[48:51]
	v_mfma_f32_16x16x32_bf16 v[40:43], v[164:167], v[216:219], v[40:43]
	v_mfma_f32_16x16x32_bf16 v[32:35], v[156:159], v[224:227], v[32:35]
	v_mfma_f32_16x16x32_bf16 v[24:27], v[164:167], v[224:227], v[24:27]
	v_mfma_f32_16x16x32_bf16 v[16:19], v[156:159], v[232:235], v[16:19]
	v_mfma_f32_16x16x32_bf16 v[8:11], v[164:167], v[232:235], v[8:11]
	v_mfma_f32_16x16x32_bf16 v[64:67], v[160:163], v[212:215], v[64:67]
	v_mfma_f32_16x16x32_bf16 v[56:59], v[168:171], v[212:215], v[56:59]
	v_mfma_f32_16x16x32_bf16 v[48:51], v[160:163], v[220:223], v[48:51]
	v_mfma_f32_16x16x32_bf16 v[40:43], v[168:171], v[220:223], v[40:43]
	v_mfma_f32_16x16x32_bf16 v[32:35], v[160:163], v[228:231], v[32:35]
	v_mfma_f32_16x16x32_bf16 v[24:27], v[168:171], v[228:231], v[24:27]
	v_mfma_f32_16x16x32_bf16 v[16:19], v[160:163], v[236:239], v[16:19]
	v_mfma_f32_16x16x32_bf16 v[8:11], v[168:171], v[236:239], v[8:11]
	s_setprio 0
	s_setprio 1
	v_mfma_f32_16x16x32_bf16 v[60:63], v[172:175], v[208:211], v[60:63]
	v_mfma_f32_16x16x32_bf16 v[52:55], v[180:183], v[208:211], v[52:55]
	v_mfma_f32_16x16x32_bf16 v[44:47], v[172:175], v[216:219], v[44:47]
	v_mfma_f32_16x16x32_bf16 v[36:39], v[180:183], v[216:219], v[36:39]
	v_mfma_f32_16x16x32_bf16 v[28:31], v[172:175], v[224:227], v[28:31]
	v_mfma_f32_16x16x32_bf16 v[20:23], v[180:183], v[224:227], v[20:23]
	v_mfma_f32_16x16x32_bf16 v[12:15], v[172:175], v[232:235], v[12:15]
	v_mfma_f32_16x16x32_bf16 v[4:7], v[180:183], v[232:235], v[4:7]
	v_mfma_f32_16x16x32_bf16 v[60:63], v[176:179], v[212:215], v[60:63]
	v_mfma_f32_16x16x32_bf16 v[52:55], v[184:187], v[212:215], v[52:55]
	v_mfma_f32_16x16x32_bf16 v[44:47], v[176:179], v[220:223], v[44:47]
	v_mfma_f32_16x16x32_bf16 v[36:39], v[184:187], v[220:223], v[36:39]
	v_mfma_f32_16x16x32_bf16 v[28:31], v[176:179], v[228:231], v[28:31]
	v_mfma_f32_16x16x32_bf16 v[20:23], v[184:187], v[228:231], v[20:23]
	v_mfma_f32_16x16x32_bf16 v[12:15], v[176:179], v[236:239], v[12:15]
	v_mfma_f32_16x16x32_bf16 v[4:7], v[184:187], v[236:239], v[4:7]
	s_setprio 0
	s_barrier
	s_mov_b32 m0, s43
	s_nop 0
	global_load_lds_dwordx4 v140, s[24:25]
	s_add_i32 s46, 0, 0x18000
	s_add_i32 s47, 0, 0x1c000
	ds_read_b128 v[156:159], v240 offset:32768
	ds_read_b128 v[160:163], v240 offset:33792
	ds_read_b128 v[164:167], v240 offset:34816
	ds_read_b128 v[168:171], v240 offset:35840
	ds_read_b128 v[172:175], v240 offset:49152
	ds_read_b128 v[176:179], v240 offset:50176
	ds_read_b128 v[180:183], v240 offset:51200
	ds_read_b128 v[184:187], v240 offset:52224
	s_add_u32 s18, s24, 0x40000
	s_addc_u32 s19, s25, 0
	s_mov_b32 m0, s48
	ds_read_b128 v[208:211], v155 offset:32768
	ds_read_b128 v[212:215], v155 offset:33792
	ds_read_b128 v[216:219], v155 offset:34816
	ds_read_b128 v[220:223], v155 offset:35840
	ds_read_b128 v[224:227], v155 offset:36864
	ds_read_b128 v[228:231], v155 offset:37888
	ds_read_b128 v[232:235], v155 offset:38912
	ds_read_b128 v[236:239], v155 offset:39936
	global_load_lds_dwordx4 v0, s[18:19]
	s_mov_b32 m0, s49
	s_nop 0
	global_load_lds_dwordx4 v140, s[18:19]
	s_waitcnt vmcnt(8)
	s_waitcnt lgkmcnt(0)
	s_barrier
	s_setprio 1
	s_waitcnt lgkmcnt(0)
	v_mfma_f32_16x16x32_bf16 v[128:131], v[156:159], v[208:211], v[128:131]
	v_mfma_f32_16x16x32_bf16 v[120:123], v[164:167], v[208:211], v[120:123]
	v_mfma_f32_16x16x32_bf16 v[112:115], v[156:159], v[216:219], v[112:115]
	v_mfma_f32_16x16x32_bf16 v[104:107], v[164:167], v[216:219], v[104:107]
	v_mfma_f32_16x16x32_bf16 v[96:99], v[156:159], v[224:227], v[96:99]
	v_mfma_f32_16x16x32_bf16 v[88:91], v[164:167], v[224:227], v[88:91]
	v_mfma_f32_16x16x32_bf16 v[80:83], v[156:159], v[232:235], v[80:83]
	v_mfma_f32_16x16x32_bf16 v[72:75], v[164:167], v[232:235], v[72:75]
	v_mfma_f32_16x16x32_bf16 v[128:131], v[160:163], v[212:215], v[128:131]
	v_mfma_f32_16x16x32_bf16 v[120:123], v[168:171], v[212:215], v[120:123]
	v_mfma_f32_16x16x32_bf16 v[112:115], v[160:163], v[220:223], v[112:115]
	v_mfma_f32_16x16x32_bf16 v[104:107], v[168:171], v[220:223], v[104:107]
	v_mfma_f32_16x16x32_bf16 v[96:99], v[160:163], v[228:231], v[96:99]
	v_mfma_f32_16x16x32_bf16 v[88:91], v[168:171], v[228:231], v[88:91]
	v_mfma_f32_16x16x32_bf16 v[80:83], v[160:163], v[236:239], v[80:83]
	v_mfma_f32_16x16x32_bf16 v[72:75], v[168:171], v[236:239], v[72:75]
	s_setprio 0
	s_setprio 1
	v_mfma_f32_16x16x32_bf16 v[124:127], v[172:175], v[208:211], v[124:127]
	v_mfma_f32_16x16x32_bf16 v[116:119], v[180:183], v[208:211], v[116:119]
	v_mfma_f32_16x16x32_bf16 v[108:111], v[172:175], v[216:219], v[108:111]
	v_mfma_f32_16x16x32_bf16 v[100:103], v[180:183], v[216:219], v[100:103]
	v_mfma_f32_16x16x32_bf16 v[92:95], v[172:175], v[224:227], v[92:95]
	v_mfma_f32_16x16x32_bf16 v[84:87], v[180:183], v[224:227], v[84:87]
	v_mfma_f32_16x16x32_bf16 v[76:79], v[172:175], v[232:235], v[76:79]
	v_mfma_f32_16x16x32_bf16 v[68:71], v[180:183], v[232:235], v[68:71]
	v_mfma_f32_16x16x32_bf16 v[124:127], v[176:179], v[212:215], v[124:127]
	v_mfma_f32_16x16x32_bf16 v[116:119], v[184:187], v[212:215], v[116:119]
	v_mfma_f32_16x16x32_bf16 v[108:111], v[176:179], v[220:223], v[108:111]
	v_mfma_f32_16x16x32_bf16 v[100:103], v[184:187], v[220:223], v[100:103]
	v_mfma_f32_16x16x32_bf16 v[92:95], v[176:179], v[228:231], v[92:95]
	v_mfma_f32_16x16x32_bf16 v[84:87], v[184:187], v[228:231], v[84:87]
	v_mfma_f32_16x16x32_bf16 v[76:79], v[176:179], v[236:239], v[76:79]
	v_mfma_f32_16x16x32_bf16 v[68:71], v[184:187], v[236:239], v[68:71]
	s_setprio 0
	s_barrier
	s_add_i32 s18, s46, s28
	s_add_u32 s100, s22, 0x80
	s_addc_u32 s101, s23, 0
	s_mov_b32 m0, s18
	ds_read_b128 v[208:211], v155 offset:49152
	ds_read_b128 v[212:215], v155 offset:50176
	ds_read_b128 v[216:219], v155 offset:51200
	ds_read_b128 v[220:223], v155 offset:52224
	ds_read_b128 v[224:227], v155 offset:53248
	ds_read_b128 v[228:231], v155 offset:54272
	ds_read_b128 v[232:235], v155 offset:55296
	ds_read_b128 v[236:239], v155 offset:56320
	global_load_lds_dwordx4 v2, s[100:101]
	s_add_i32 m0, s18, 0x2000
	s_add_u32 s18, s22, 0x40080
	s_addc_u32 s19, s23, 0
	s_add_i32 s22, s47, s28
	global_load_lds_dwordx4 v142, s[100:101]
	s_mov_b32 m0, s22
	s_nop 0
	global_load_lds_dwordx4 v2, s[18:19]
	s_add_i32 m0, s22, 0x2000
	s_nop 0
	global_load_lds_dwordx4 v142, s[18:19]
	s_add_u32 s100, s24, 0x80
	s_addc_u32 s101, s25, 0
	s_mov_b32 m0, s50
	s_nop 0
	global_load_lds_dwordx4 v0, s[100:101]
	s_waitcnt vmcnt(7)
	s_waitcnt lgkmcnt(0)
	s_barrier
	s_setprio 1
	s_waitcnt lgkmcnt(0)
	v_mfma_f32_16x16x32_bf16 v[64:67], v[156:159], v[208:211], v[64:67]
	v_mfma_f32_16x16x32_bf16 v[56:59], v[164:167], v[208:211], v[56:59]
	v_mfma_f32_16x16x32_bf16 v[48:51], v[156:159], v[216:219], v[48:51]
	v_mfma_f32_16x16x32_bf16 v[40:43], v[164:167], v[216:219], v[40:43]
	v_mfma_f32_16x16x32_bf16 v[32:35], v[156:159], v[224:227], v[32:35]
	v_mfma_f32_16x16x32_bf16 v[24:27], v[164:167], v[224:227], v[24:27]
	v_mfma_f32_16x16x32_bf16 v[16:19], v[156:159], v[232:235], v[16:19]
	v_mfma_f32_16x16x32_bf16 v[8:11], v[164:167], v[232:235], v[8:11]
	v_mfma_f32_16x16x32_bf16 v[64:67], v[160:163], v[212:215], v[64:67]
	v_mfma_f32_16x16x32_bf16 v[56:59], v[168:171], v[212:215], v[56:59]
	v_mfma_f32_16x16x32_bf16 v[48:51], v[160:163], v[220:223], v[48:51]
	v_mfma_f32_16x16x32_bf16 v[40:43], v[168:171], v[220:223], v[40:43]
	v_mfma_f32_16x16x32_bf16 v[32:35], v[160:163], v[228:231], v[32:35]
	v_mfma_f32_16x16x32_bf16 v[24:27], v[168:171], v[228:231], v[24:27]
	v_mfma_f32_16x16x32_bf16 v[16:19], v[160:163], v[236:239], v[16:19]
	v_mfma_f32_16x16x32_bf16 v[8:11], v[168:171], v[236:239], v[8:11]
	s_setprio 0
	s_setprio 1
	v_mfma_f32_16x16x32_bf16 v[60:63], v[172:175], v[208:211], v[60:63]
	v_mfma_f32_16x16x32_bf16 v[52:55], v[180:183], v[208:211], v[52:55]
	v_mfma_f32_16x16x32_bf16 v[44:47], v[172:175], v[216:219], v[44:47]
	v_mfma_f32_16x16x32_bf16 v[36:39], v[180:183], v[216:219], v[36:39]
	v_mfma_f32_16x16x32_bf16 v[28:31], v[172:175], v[224:227], v[28:31]
	v_mfma_f32_16x16x32_bf16 v[20:23], v[180:183], v[224:227], v[20:23]
	v_mfma_f32_16x16x32_bf16 v[12:15], v[172:175], v[232:235], v[12:15]
	v_mfma_f32_16x16x32_bf16 v[4:7], v[180:183], v[232:235], v[4:7]
	v_mfma_f32_16x16x32_bf16 v[60:63], v[176:179], v[212:215], v[60:63]
	v_mfma_f32_16x16x32_bf16 v[52:55], v[184:187], v[212:215], v[52:55]
	v_mfma_f32_16x16x32_bf16 v[44:47], v[176:179], v[220:223], v[44:47]
	v_mfma_f32_16x16x32_bf16 v[36:39], v[184:187], v[220:223], v[36:39]
	v_mfma_f32_16x16x32_bf16 v[28:31], v[176:179], v[228:231], v[28:31]
	v_mfma_f32_16x16x32_bf16 v[20:23], v[184:187], v[228:231], v[20:23]
	v_mfma_f32_16x16x32_bf16 v[12:15], v[176:179], v[236:239], v[12:15]
	v_mfma_f32_16x16x32_bf16 v[4:7], v[184:187], v[236:239], v[4:7]
	s_setprio 0
	s_barrier
	s_add_i32 s15, s15, 2
	s_add_u32 s44, s44, 0x100
	s_addc_u32 s45, s45, 0
	s_add_u32 s13, s13, 0x100
	s_addc_u32 s14, s14, 0
	s_cmp_gt_u32 s15, 13
	s_cbranch_scc0 .LBB0_98
	s_lshl_b32 s5, s42, 8
	s_and_b64 vcc, exec, s[2:3]
	s_cbranch_vccz .LBB0_101
	v_or_b32_e32 v148, s5, v152
	v_ashrrev_i32_e32 v149, 31, v148
	v_readlane_b32 s10, v255, 11
	v_lshlrev_b64 v[148:149], 6, v[148:149]
	v_readlane_b32 s11, v255, 12
	s_nop 1
	v_lshl_add_u64 v[148:149], s[10:11], 0, v[148:149]
	global_load_dwordx4 v[156:159], v[148:149], off
	global_load_dwordx4 v[160:163], v[148:149], off offset:32
	global_load_dwordx4 v[164:167], v[148:149], off offset:16
	global_load_dwordx4 v[168:171], v[148:149], off offset:48
	s_barrier
